# v22 = v21 + static s_setprio 1 for waves 4-7 (real wave index) during the causal attention units
# speedup vs baseline: 1.0016x; 1.0016x over previous
.LBB0_547:
	v_readlane_b32 s101, v246, 60
	s_nop 0
	s_cmp_lt_u32 s101, 4
	s_cbranch_scc1 .Lprio_skip
	s_setprio 1

.LBB0_668:
	s_setprio 0
	v_readlane_b32 s94, v246, 53
	s_ashr_i32 s4, s94, 7
	s_ashr_i32 s5, s4, 31
	s_lshl_b64 s[0:1], s[4:5], 22
	v_readlane_b32 s6, v244, 19
	v_readlane_b32 s7, v244, 20
	s_add_u32 s0, s6, s0
	s_addc_u32 s1, s7, s1
	s_lshl_b32 s2, s72, 6
	s_and_b32 s2, s2, 0xc0
	s_lshl_b32 s12, s2, 1
	s_add_u32 s10, s0, s12
	s_addc_u32 s11, s1, 0
	s_lshl_b64 s[0:1], s[4:5], 17
	s_add_u32 s0, s6, s0
	s_addc_u32 s1, s7, s1
	s_add_u32 s13, s0, s12
	s_addc_u32 s14, s1, 0
	s_add_u32 s0, s13, 0x600000
	s_addc_u32 s1, s14, 0
	s_add_u32 s8, s13, 0x640000
	s_addc_u32 s9, s14, 0
	s_lshl_b32 s2, s70, 8
	s_mov_b32 s3, 0
	s_add_i32 s2, s2, s71
	s_lshl_b64 s[6:7], s[2:3], 9
	s_add_u32 s6, s10, s6
	s_addc_u32 s7, s11, s7
	v_readlane_b32 s10, v246, 55
	s_cmp_lg_u32 0, -1
	v_mov_b32_e32 v149, 0
	v_lshl_add_u32 v33, v148, 9, s10
	v_readlane_b32 s10, v246, 56
	v_lshlrev_b32_e32 v148, 9, v170
	s_nop 0
	v_add_lshl_u32 v0, v181, s10, 9
	s_cselect_b32 s10, 0, 0
	v_lshl_add_u32 v96, v182, 1, v0
	s_add_i32 s15, s73, s10
	s_mov_b32 m0, s15
	s_nop 0
	global_load_lds_dwordx4 v33, s[0:1]
	v_lshl_add_u64 v[0:1], s[6:7], 0, v[148:149]
	s_mov_b32 m0, s33
	s_nop 0
	global_load_lds_dwordx4 v96, s[8:9]
	v_lshl_add_u64 v[0:1], v[150:151], 1, v[0:1]
	s_mov_b32 s6, 0xd000000
	s_add_u32 s10, s13, 0x608000
	v_add_co_u32_e32 v2, vcc, s6, v0
	s_addc_u32 s11, s14, 0
	s_add_i32 s16, s15, 0x3000
	s_mov_b32 m0, s16
	s_nop 0
	global_load_lds_dwordx4 v33, s[10:11]
	v_addc_co_u32_e32 v3, vcc, 0, v1, vcc
	global_load_dwordx4 v[136:139], v[2:3], off
	s_mov_b64 s[6:7], 0xd000000
	v_lshl_add_u64 v[0:1], v[0:1], 0, s[6:7]
	global_load_dwordx4 v[132:135], v[0:1], off offset:32
	global_load_dwordx4 v[128:131], v[0:1], off offset:64
	global_load_dwordx4 v[124:127], v[0:1], off offset:96
	s_add_u32 s6, s13, 0x610000
	s_addc_u32 s7, s14, 0
	s_addk_i32 s15, 0x6000
	s_mov_b32 m0, s15
	s_nop 0
	global_load_lds_dwordx4 v33, s[6:7]
	s_waitcnt vmcnt(3)
	s_barrier
	ds_read_b128 v[0:3], v179
	ds_read_b128 v[34:37], v179 offset:2048
	s_mov_b32 s10, 0x41400000
	s_waitcnt vmcnt(3) lgkmcnt(1)
	v_mfma_f32_32x32x16_bf16 v[16:31], v[0:3], v[136:139], 0
	ds_read_b128 v[0:3], v179 offset:512
	s_waitcnt vmcnt(2) lgkmcnt(1)
	v_mfma_f32_32x32x16_bf16 v[16:31], v[34:37], v[132:135], v[16:31]
	ds_read_b128 v[34:37], v179 offset:2560
	s_waitcnt lgkmcnt(1)
	v_mfma_f32_32x32x16_bf16 v[0:15], v[0:3], v[136:139], 0
	s_waitcnt lgkmcnt(0)
	v_mfma_f32_32x32x16_bf16 v[0:15], v[34:37], v[132:135], v[0:15]
	ds_read_b128 v[34:37], v179 offset:4096
	s_waitcnt vmcnt(1) lgkmcnt(0)
	v_mfma_f32_32x32x16_bf16 v[16:31], v[34:37], v[128:131], v[16:31]
	ds_read_b128 v[34:37], v179 offset:4608
	s_waitcnt lgkmcnt(0)
	v_mfma_f32_32x32x16_bf16 v[0:15], v[34:37], v[128:131], v[0:15]
	ds_read_b128 v[34:37], v179 offset:6144
	s_waitcnt vmcnt(0) lgkmcnt(0)
	v_mfma_f32_32x32x16_bf16 v[16:31], v[34:37], v[124:127], v[16:31]
	ds_read_b128 v[34:37], v179 offset:6656
	s_waitcnt lgkmcnt(0)
	v_mfma_f32_32x32x16_bf16 v[0:15], v[34:37], v[124:127], v[0:15]
	s_nop 8
	v_max_f32_e32 v32, v17, v17
	v_max_f32_e32 v34, v16, v16
	v_max_f32_e32 v32, v34, v32
	v_max3_f32 v35, v18, v19, v1
	v_max3_f32 v32, v32, v0, v2
	v_max3_f32 v34, v35, v22, v23
	v_max3_f32 v32, v32, v3, v20
	v_max3_f32 v34, v34, v6, v7
	v_max3_f32 v32, v32, v21, v4
	v_max3_f32 v34, v34, v26, v27
	v_max3_f32 v32, v32, v5, v24
	v_max3_f32 v34, v34, v10, v11
	v_max3_f32 v32, v32, v25, v8
	v_max3_f32 v34, v34, v30, v31
	v_max3_f32 v32, v32, v9, v28
	v_max3_f32 v34, v34, v14, v15
	v_max3_f32 v32, v32, v29, v12
	v_max3_f32 v32, v32, v13, v34
	v_mov_b32_e32 v34, v32
	s_nop 1
	v_permlane32_swap_b32_e32 v32, v34
	v_max_f32_e32 v34, v34, v34
	v_max_f32_e32 v32, v32, v32
	v_max_f32_e32 v32, v32, v34
	v_cmp_gt_f32_e64 vcc, |v32|, s10
	s_cmp_lg_u64 vcc, 0
	s_cselect_b64 s[6:7], -1, 0
	s_cbranch_vccnz .LBB0_1425
